# final norm loop: six serialized per-iteration gain loads hoisted out of the loop (prologue de-serialisation); on top of previous best
# baseline (speedup 1.0000x reference)
; #define UNPK8N(dst, u) do { dst[0] = bflo(u.x); dst[1] = bfhi(u.x); dst[2] = bflo(u.y); dst[3] = bfhi(u.y); dst[4] = bflo(u.z); dst[5] = bfhi(u.z); dst[6] = bflo(u.w); dst[7] = bfhi(u.w); } while (0)
; __device__ __forceinline__ void final_norm3(const bf16_t* hsrc, const bf16_t* dsrc, float dscale, float* dst, const float* gain, int rows, int wg, int nwg) {
;     const int lane = threadIdx.x & 63, wid = threadIdx.x >> 6;
;     for (int row = wg * 8 + wid; row < rows; row += nwg * 8) {
;         const u32x4* ph = (const u32x4*)(hsrc + (size_t)row * D); const u32x4* pd = (const u32x4*)(dsrc + (size_t)row * D);
;         float v[4][8]; float ss = 0.f;
; #pragma unroll
;         for (int i = 0; i < 4; ++i) { const u32x4 a = ph[lane + 64 * i], b = pd[lane + 64 * i]; float x[8], y[8]; UNPK8N(x, a); UNPK8N(y, b);
; #pragma unroll
;             for (int e = 0; e < 8; ++e) { v[i][e] = x[e] + dscale * y[e]; ss += v[i][e] * v[i][e]; } }
.LBB0_1557:
	s_or_b64 exec, exec, s[2:3]
	s_waitcnt lgkmcnt(0)
	s_barrier
	s_and_saveexec_b64 s[2:3], s[4:5]
	s_cbranch_execz .LBB0_1560
	v_mbcnt_hi_u32_b32 v2, -1, v1
	v_and_b32_e32 v1, 64, v2
	v_add_u32_e32 v3, 64, v1
	v_xor_b32_e32 v1, 32, v2
	v_cmp_lt_i32_e32 vcc, v1, v3
	v_xor_b32_e32 v4, 16, v2
	s_load_dwordx4 s[4:7], s[0:1], 0x118
	v_cndmask_b32_e32 v1, v2, v1, vcc
	v_cmp_lt_i32_e32 vcc, v4, v3
	v_lshlrev_b32_e32 v12, 5, v160
	v_mov_b32_e32 v13, 0
	v_cndmask_b32_e32 v4, v2, v4, vcc
	v_lshlrev_b32_e32 v14, 2, v4
	v_xor_b32_e32 v4, 8, v2
	v_cmp_lt_i32_e32 vcc, v4, v3
	v_lshlrev_b64 v[10:11], 12, v[162:163]
	v_lshlrev_b64 v[20:21], 13, v[162:163]
	v_cndmask_b32_e32 v4, v2, v4, vcc
	v_lshlrev_b32_e32 v15, 2, v4
	v_xor_b32_e32 v4, 4, v2
	v_cmp_lt_i32_e32 vcc, v4, v3
	v_mov_b32_e32 v5, v13
	v_or_b32_e32 v6, 0x1000, v12
	v_cndmask_b32_e32 v4, v2, v4, vcc
	v_lshlrev_b32_e32 v16, 2, v4
	v_xor_b32_e32 v4, 2, v2
	v_cmp_lt_i32_e32 vcc, v4, v3
	v_mov_b32_e32 v7, v13
	v_or_b32_e32 v8, 0x1800, v12
	v_cndmask_b32_e32 v4, v2, v4, vcc
	v_lshlrev_b32_e32 v17, 2, v4
	v_xor_b32_e32 v4, 1, v2
	v_cmp_lt_i32_e32 vcc, v4, v3
	v_mov_b32_e32 v9, v13
	v_lshl_or_b32 v10, v160, 4, v10
	v_cndmask_b32_e32 v2, v2, v4, vcc
	v_or_b32_e32 v4, 0x800, v12
	v_or_b32_e32 v20, v20, v12
	v_lshlrev_b32_e32 v18, 2, v2
	s_waitcnt lgkmcnt(0)
	v_lshl_add_u64 v[2:3], s[4:5], 0, v[12:13]
	v_lshl_add_u64 v[4:5], s[4:5], 0, v[4:5]
	v_lshl_add_u64 v[6:7], s[4:5], 0, v[6:7]
	v_lshl_add_u64 v[8:9], s[4:5], 0, v[8:9]
	v_lshl_add_u64 v[10:11], s[26:27], 0, v[10:11]
	s_mov_b64 s[0:1], 0x1ec00c00
	s_ashr_i32 s43, s42, 31
	v_lshl_add_u64 v[12:13], s[6:7], 0, v[20:21]
	s_mov_b64 s[4:5], 0x1000
	v_lshlrev_b32_e32 v1, 2, v1
	v_lshl_add_u64 v[10:11], v[10:11], 0, s[0:1]
	s_lshl_b64 s[0:1], s[42:43], 12
	v_lshl_add_u64 v[12:13], v[12:13], 0, s[4:5]
	s_lshl_b64 s[4:5], s[42:43], 13
	s_mov_b64 s[6:7], 0
	v_mov_b32_e32 v19, 0x358637bd
	s_mov_b32 s8, 0x800000
	s_movk_i32 s9, 0x3fff
	global_load_dwordx4 v[200:203], v[4:5], off
	global_load_dwordx4 v[204:207], v[4:5], off offset:16
	global_load_dwordx4 v[208:211], v[6:7], off
	global_load_dwordx4 v[212:215], v[6:7], off offset:16
	global_load_dwordx4 v[216:219], v[8:9], off
	global_load_dwordx4 v[220:223], v[8:9], off offset:16
	s_waitcnt vmcnt(0)
.LBB0_1559:
	v_add_co_u32_e32 v60, vcc, 0xfc000000, v10
	global_load_dwordx4 v[20:23], v[10:11], off offset:-3072
	global_load_dwordx4 v[24:27], v[10:11], off offset:-2048
	global_load_dwordx4 v[28:31], v[10:11], off offset:-1024
	global_load_dwordx4 v[32:35], v[10:11], off
	v_addc_co_u32_e32 v61, vcc, -1, v11, vcc
	global_load_dwordx4 v[36:39], v[2:3], off offset:16
	global_load_dwordx4 v[40:43], v[2:3], off
	global_load_dwordx4 v[44:47], v[60:61], off offset:-3072
	global_load_dwordx4 v[48:51], v[60:61], off offset:-2048
	global_load_dwordx4 v[52:55], v[60:61], off offset:-1024
	global_load_dwordx4 v[56:59], v[60:61], off
	v_add_u32_e32 v162, s42, v162
	v_lshl_add_u64 v[10:11], v[10:11], 0, s[0:1]
	s_waitcnt vmcnt(9)
	v_lshlrev_b32_e32 v60, 16, v20
	v_and_b32_e32 v61, 0xffff0000, v20
	v_lshlrev_b32_e32 v20, 16, v21
	v_and_b32_e32 v21, 0xffff0000, v21
	s_waitcnt vmcnt(3)
	v_lshlrev_b32_e32 v76, 16, v44
	v_and_b32_e32 v77, 0xffff0000, v44
	v_lshlrev_b32_e32 v64, 16, v24
	v_and_b32_e32 v65, 0xffff0000, v24
	v_lshlrev_b32_e32 v24, 16, v25
	v_and_b32_e32 v25, 0xffff0000, v25
	v_lshlrev_b32_e32 v44, 16, v45
	v_and_b32_e32 v45, 0xffff0000, v45
	s_waitcnt vmcnt(2)
	v_lshlrev_b32_e32 v80, 16, v48
	v_and_b32_e32 v81, 0xffff0000, v48
	v_lshlrev_b32_e32 v48, 16, v49
	v_and_b32_e32 v49, 0xffff0000, v49
	v_pk_fma_f32 v[60:61], v[60:61], 0.5, v[76:77] op_sel_hi:[1,0,1]
	v_lshlrev_b32_e32 v66, 16, v26
	v_and_b32_e32 v67, 0xffff0000, v26
	v_lshlrev_b32_e32 v26, 16, v27
	v_and_b32_e32 v27, 0xffff0000, v27
	v_lshlrev_b32_e32 v82, 16, v50
	v_and_b32_e32 v83, 0xffff0000, v50
	v_lshlrev_b32_e32 v50, 16, v51
	v_and_b32_e32 v51, 0xffff0000, v51
	v_pk_fma_f32 v[20:21], v[20:21], 0.5, v[44:45] op_sel_hi:[1,0,1]
	v_pk_fma_f32 v[48:49], v[24:25], 0.5, v[48:49] op_sel_hi:[1,0,1]
	v_pk_mul_f32 v[24:25], v[60:61], v[60:61]
	v_lshlrev_b32_e32 v62, 16, v22
	v_and_b32_e32 v63, 0xffff0000, v22
	v_lshlrev_b32_e32 v78, 16, v46
	v_and_b32_e32 v79, 0xffff0000, v46
	v_pk_fma_f32 v[50:51], v[26:27], 0.5, v[50:51] op_sel_hi:[1,0,1]
	v_pk_mul_f32 v[26:27], v[20:21], v[20:21]
	v_add_f32_e32 v24, v24, v25
	v_lshlrev_b32_e32 v74, 16, v34
	v_and_b32_e32 v75, 0xffff0000, v34
	v_lshlrev_b32_e32 v34, 16, v35
	v_and_b32_e32 v35, 0xffff0000, v35
	s_waitcnt vmcnt(0)
; __device__ __forceinline__ void final_norm3(const bf16_t* hsrc, const bf16_t* dsrc, float dscale, float* dst, const float* gain, int rows, int wg, int nwg) {
;     ...
;         ss = wave_sum(ss);
;         const float rs = rsqrtf(ss * (1.f / D) + 1e-6f);
; #pragma unroll
;         for (int i = 0; i < 4; ++i) {
;             const f32x4 g0 = ((const f32x4*)gain)[(lane + 64 * i) * 2], g1 = ((const f32x4*)gain)[(lane + 64 * i) * 2 + 1];
;             f32x4* q = (f32x4*)(dst + (size_t)row * D + (lane + 64 * i) * 8);
;             q[0] = (f32x4){v[i][0], v[i][1], v[i][2], v[i][3]} * rs * g0; q[1] = (f32x4){v[i][4], v[i][5], v[i][6], v[i][7]} * rs * g1;
;         }
	v_lshlrev_b32_e32 v90, 16, v58
	v_and_b32_e32 v91, 0xffff0000, v58
	v_lshlrev_b32_e32 v58, 16, v59
	v_and_b32_e32 v59, 0xffff0000, v59
	v_pk_fma_f32 v[44:45], v[62:63], 0.5, v[78:79] op_sel_hi:[1,0,1]
	v_add_f32_e32 v24, v26, v24
	v_lshlrev_b32_e32 v22, 16, v23
	v_and_b32_e32 v23, 0xffff0000, v23
	v_lshlrev_b32_e32 v46, 16, v47
	v_and_b32_e32 v47, 0xffff0000, v47
	v_pk_fma_f32 v[34:35], v[34:35], 0.5, v[58:59] op_sel_hi:[1,0,1]
	v_pk_mul_f32 v[58:59], v[44:45], v[44:45]
	v_add_f32_e32 v24, v27, v24
	v_pk_fma_f32 v[22:23], v[22:23], 0.5, v[46:47] op_sel_hi:[1,0,1]
	v_add_f32_e32 v24, v58, v24
	v_pk_fma_f32 v[62:63], v[66:67], 0.5, v[82:83] op_sel_hi:[1,0,1]
	v_pk_mul_f32 v[66:67], v[22:23], v[22:23]
	v_add_f32_e32 v24, v59, v24
	v_lshlrev_b32_e32 v68, 16, v28
	v_and_b32_e32 v69, 0xffff0000, v28
	v_lshlrev_b32_e32 v84, 16, v52
	v_and_b32_e32 v85, 0xffff0000, v52
	v_pk_fma_f32 v[46:47], v[64:65], 0.5, v[80:81] op_sel_hi:[1,0,1]
	v_add_f32_e32 v24, v66, v24
	v_pk_fma_f32 v[64:65], v[68:69], 0.5, v[84:85] op_sel_hi:[1,0,1]
	v_pk_mul_f32 v[68:69], v[46:47], v[46:47]
	v_add_f32_e32 v24, v67, v24
	v_lshlrev_b32_e32 v28, 16, v29
	v_and_b32_e32 v29, 0xffff0000, v29
	v_lshlrev_b32_e32 v70, 16, v30
	v_and_b32_e32 v71, 0xffff0000, v30
	v_lshlrev_b32_e32 v52, 16, v53
	v_and_b32_e32 v53, 0xffff0000, v53
	v_lshlrev_b32_e32 v86, 16, v54
	v_and_b32_e32 v87, 0xffff0000, v54
	v_add_f32_e32 v24, v68, v24
	v_pk_fma_f32 v[28:29], v[28:29], 0.5, v[52:53] op_sel_hi:[1,0,1]
	v_pk_fma_f32 v[52:53], v[70:71], 0.5, v[86:87] op_sel_hi:[1,0,1]
	v_pk_mul_f32 v[70:71], v[48:49], v[48:49]
	v_add_f32_e32 v24, v69, v24
	v_lshlrev_b32_e32 v30, 16, v31
	v_and_b32_e32 v31, 0xffff0000, v31
	v_lshlrev_b32_e32 v72, 16, v32
	v_and_b32_e32 v73, 0xffff0000, v32
	v_lshlrev_b32_e32 v54, 16, v55
	v_and_b32_e32 v55, 0xffff0000, v55
	v_lshlrev_b32_e32 v88, 16, v56
	v_and_b32_e32 v89, 0xffff0000, v56
	v_add_f32_e32 v24, v70, v24
	v_pk_fma_f32 v[30:31], v[30:31], 0.5, v[54:55] op_sel_hi:[1,0,1]
	v_pk_fma_f32 v[54:55], v[72:73], 0.5, v[88:89] op_sel_hi:[1,0,1]
	v_pk_mul_f32 v[72:73], v[62:63], v[62:63]
	v_add_f32_e32 v24, v71, v24
	v_lshlrev_b32_e32 v32, 16, v33
	v_and_b32_e32 v33, 0xffff0000, v33
	v_lshlrev_b32_e32 v56, 16, v57
	v_and_b32_e32 v57, 0xffff0000, v57
	v_add_f32_e32 v24, v72, v24
	v_pk_fma_f32 v[32:33], v[32:33], 0.5, v[56:57] op_sel_hi:[1,0,1]
	v_pk_fma_f32 v[56:57], v[74:75], 0.5, v[90:91] op_sel_hi:[1,0,1]
	v_pk_mul_f32 v[74:75], v[50:51], v[50:51]
	v_add_f32_e32 v24, v73, v24
	v_add_f32_e32 v24, v74, v24
	v_pk_mul_f32 v[76:77], v[64:65], v[64:65]
	v_add_f32_e32 v24, v75, v24
	v_add_f32_e32 v24, v76, v24
	v_pk_mul_f32 v[78:79], v[28:29], v[28:29]
	v_add_f32_e32 v24, v77, v24
	v_add_f32_e32 v24, v78, v24
	v_pk_mul_f32 v[80:81], v[52:53], v[52:53]
	v_add_f32_e32 v24, v79, v24
	v_add_f32_e32 v24, v80, v24
	v_pk_mul_f32 v[82:83], v[30:31], v[30:31]
	v_add_f32_e32 v24, v81, v24
	v_add_f32_e32 v24, v82, v24
	v_pk_mul_f32 v[84:85], v[54:55], v[54:55]
	v_add_f32_e32 v24, v83, v24
	v_add_f32_e32 v24, v84, v24
	v_pk_mul_f32 v[86:87], v[32:33], v[32:33]
	v_add_f32_e32 v24, v85, v24
	v_add_f32_e32 v24, v86, v24
	v_pk_mul_f32 v[88:89], v[56:57], v[56:57]
	v_add_f32_e32 v24, v87, v24
	v_add_f32_e32 v24, v88, v24
	v_pk_mul_f32 v[90:91], v[34:35], v[34:35]
	v_add_f32_e32 v24, v89, v24
	v_add_f32_e32 v24, v90, v24
	v_add_f32_e32 v24, v91, v24
	ds_bpermute_b32 v25, v1, v24
	s_waitcnt lgkmcnt(0)
	v_add_f32_e32 v24, v24, v25
	ds_bpermute_b32 v25, v14, v24
	s_waitcnt lgkmcnt(0)
	v_add_f32_e32 v24, v24, v25
	ds_bpermute_b32 v25, v15, v24
	s_waitcnt lgkmcnt(0)
	v_add_f32_e32 v24, v24, v25
	ds_bpermute_b32 v25, v16, v24
	s_waitcnt lgkmcnt(0)
	v_add_f32_e32 v24, v24, v25
	ds_bpermute_b32 v25, v17, v24
	s_waitcnt lgkmcnt(0)
	v_add_f32_e32 v24, v24, v25
	ds_bpermute_b32 v25, v18, v24
	s_waitcnt lgkmcnt(0)
	v_add_f32_e32 v24, v24, v25
	v_fmamk_f32 v24, v24, 0x3a000000, v19
	v_mul_f32_e32 v25, 0x4b800000, v24
	v_cmp_gt_f32_e32 vcc, s8, v24
	s_nop 1
	v_cndmask_b32_e32 v24, v24, v25, vcc
	v_rsq_f32_e32 v24, v24
	s_nop 0
	v_mul_f32_e32 v25, 0x45800000, v24
	v_cndmask_b32_e32 v58, v24, v25, vcc
	v_pk_mul_f32 v[24:25], v[60:61], v[58:59] op_sel_hi:[1,0]
	v_pk_mul_f32 v[20:21], v[20:21], v[58:59] op_sel_hi:[1,0]
	v_pk_mul_f32 v[44:45], v[44:45], v[58:59] op_sel_hi:[1,0]
	v_pk_mul_f32 v[26:27], v[22:23], v[58:59] op_sel_hi:[1,0]
	v_pk_mul_f32 v[22:23], v[42:43], v[20:21]
	v_pk_mul_f32 v[20:21], v[40:41], v[24:25]
	v_pk_mul_f32 v[26:27], v[38:39], v[26:27]
	v_pk_mul_f32 v[24:25], v[36:37], v[44:45]
	global_store_dwordx4 v[12:13], v[20:23], off offset:-4096
	global_store_dwordx4 v[12:13], v[24:27], off offset:-4080
	v_pk_mul_f32 v[36:37], v[48:49], v[58:59] op_sel_hi:[1,0]
	v_pk_mul_f32 v[38:39], v[46:47], v[58:59] op_sel_hi:[1,0]
	v_pk_mul_f32 v[40:41], v[50:51], v[58:59] op_sel_hi:[1,0]
	v_pk_mul_f32 v[42:43], v[62:63], v[58:59] op_sel_hi:[1,0]
	v_pk_mul_f32 v[28:29], v[28:29], v[58:59] op_sel_hi:[1,0]
	v_pk_mul_f32 v[30:31], v[30:31], v[58:59] op_sel_hi:[1,0]
	v_cmp_lt_i32_e32 vcc, s9, v162
	s_or_b64 s[6:7], vcc, s[6:7]
	v_pk_mul_f32 v[20:21], v[200:201], v[38:39]
	v_pk_mul_f32 v[22:23], v[202:203], v[36:37]
	v_pk_mul_f32 v[24:25], v[204:205], v[42:43]
	v_pk_mul_f32 v[26:27], v[206:207], v[40:41]
	global_store_dwordx4 v[12:13], v[20:23], off offset:-2048
	global_store_dwordx4 v[12:13], v[24:27], off offset:-2032
	v_pk_mul_f32 v[36:37], v[64:65], v[58:59] op_sel_hi:[1,0]
	v_pk_mul_f32 v[38:39], v[52:53], v[58:59] op_sel_hi:[1,0]
	v_pk_mul_f32 v[20:21], v[208:209], v[36:37]
	v_pk_mul_f32 v[22:23], v[210:211], v[28:29]
	v_pk_mul_f32 v[24:25], v[212:213], v[38:39]
	v_pk_mul_f32 v[26:27], v[214:215], v[30:31]
	global_store_dwordx4 v[12:13], v[20:23], off
	global_store_dwordx4 v[12:13], v[24:27], off offset:16
	v_pk_mul_f32 v[28:29], v[32:33], v[58:59] op_sel_hi:[1,0]
	v_pk_mul_f32 v[30:31], v[54:55], v[58:59] op_sel_hi:[1,0]
	v_pk_mul_f32 v[32:33], v[34:35], v[58:59] op_sel_hi:[1,0]
	v_pk_mul_f32 v[34:35], v[56:57], v[58:59] op_sel_hi:[1,0]
	s_nop 1
	v_pk_mul_f32 v[20:21], v[216:217], v[30:31]
	v_pk_mul_f32 v[22:23], v[218:219], v[28:29]
	v_pk_mul_f32 v[24:25], v[220:221], v[34:35]
	v_pk_mul_f32 v[26:27], v[222:223], v[32:33]
	global_store_dwordx4 v[12:13], v[20:23], off offset:2048
	global_store_dwordx4 v[12:13], v[24:27], off offset:2064
	v_lshl_add_u64 v[12:13], v[12:13], 0, s[4:5]
	s_andn2_b64 exec, exec, s[6:7]
	s_cbranch_execnz .LBB0_1559
